# adds dwordx4 epilogue stores (v_permlane32_swap pairing) to the MLA attention rewrite with deferred-max rescale
# speedup vs baseline: 1.0124x; 1.0001x over previous
.LBB0_428:
	ds_bpermute_b32 v1, v246, v225
	s_mov_b64 s[4:5], 0
	s_waitcnt lgkmcnt(0)
	v_add_f32_e32 v1, v225, v1
	v_div_scale_f32 v2, s[2:3], v1, v1, 1.0
	v_rcp_f32_e32 v3, v2
	s_nop 0
	v_fma_f32 v4, -v2, v3, 1.0
	v_fmac_f32_e32 v3, v4, v3
	v_div_scale_f32 v4, vcc, 1.0, v1, 1.0
	v_mul_f32_e32 v5, v4, v3
	v_fma_f32 v6, -v2, v5, v4
	v_fmac_f32_e32 v5, v6, v3
	v_fma_f32 v2, -v2, v5, v4
	v_div_fmas_f32 v2, v2, v3, v5
	v_div_fixup_f32 v2, v2, v1, 1.0
	v_lshlrev_b64 v[4:5], 12, v[222:223]
	v_lshl_add_u64 v[4:5], v[214:215], 0, v[4:5]
	v_add_co_u32_e32 v4, vcc, v168, v4
	s_nop 1
	v_addc_co_u32_e32 v5, vcc, 0, v5, vcc
	v_pk_mul_f32 v[8:9], v[96:97], v[2:3] op_sel_hi:[1,0]
	v_pk_mul_f32 v[10:11], v[98:99], v[2:3] op_sel_hi:[1,0]
	v_pk_mul_f32 v[12:13], v[100:101], v[2:3] op_sel_hi:[1,0]
	v_pk_mul_f32 v[14:15], v[102:103], v[2:3] op_sel_hi:[1,0]
	v_cvt_pk_bf16_f32 v8, v8, v9
	v_cvt_pk_bf16_f32 v9, v10, v11
	v_cvt_pk_bf16_f32 v10, v12, v13
	v_cvt_pk_bf16_f32 v11, v14, v15
	s_nop 1
	v_permlane32_swap_b32_e32 v8, v10
	v_permlane32_swap_b32_e32 v9, v11
	global_store_dwordx4 v[4:5], v[8:11], off
	v_pk_mul_f32 v[16:17], v[104:105], v[2:3] op_sel_hi:[1,0]
	v_pk_mul_f32 v[18:19], v[106:107], v[2:3] op_sel_hi:[1,0]
	v_pk_mul_f32 v[20:21], v[108:109], v[2:3] op_sel_hi:[1,0]
	v_pk_mul_f32 v[22:23], v[110:111], v[2:3] op_sel_hi:[1,0]
	v_cvt_pk_bf16_f32 v16, v16, v17
	v_cvt_pk_bf16_f32 v17, v18, v19
	v_cvt_pk_bf16_f32 v18, v20, v21
	v_cvt_pk_bf16_f32 v19, v22, v23
	s_nop 1
	v_permlane32_swap_b32_e32 v16, v18
	v_permlane32_swap_b32_e32 v17, v19
	global_store_dwordx4 v[4:5], v[16:19], off offset:32
	v_pk_mul_f32 v[8:9], v[80:81], v[2:3] op_sel_hi:[1,0]
	v_pk_mul_f32 v[10:11], v[82:83], v[2:3] op_sel_hi:[1,0]
	v_pk_mul_f32 v[12:13], v[84:85], v[2:3] op_sel_hi:[1,0]
	v_pk_mul_f32 v[14:15], v[86:87], v[2:3] op_sel_hi:[1,0]
	v_cvt_pk_bf16_f32 v8, v8, v9
	v_cvt_pk_bf16_f32 v9, v10, v11
	v_cvt_pk_bf16_f32 v10, v12, v13
	v_cvt_pk_bf16_f32 v11, v14, v15
	s_nop 1
	v_permlane32_swap_b32_e32 v8, v10
	v_permlane32_swap_b32_e32 v9, v11
	global_store_dwordx4 v[4:5], v[8:11], off offset:64
	v_pk_mul_f32 v[16:17], v[88:89], v[2:3] op_sel_hi:[1,0]
	v_pk_mul_f32 v[18:19], v[90:91], v[2:3] op_sel_hi:[1,0]
	v_pk_mul_f32 v[20:21], v[92:93], v[2:3] op_sel_hi:[1,0]
	v_pk_mul_f32 v[22:23], v[94:95], v[2:3] op_sel_hi:[1,0]
	v_cvt_pk_bf16_f32 v16, v16, v17
	v_cvt_pk_bf16_f32 v17, v18, v19
	v_cvt_pk_bf16_f32 v18, v20, v21
	v_cvt_pk_bf16_f32 v19, v22, v23
	s_nop 1
	v_permlane32_swap_b32_e32 v16, v18
	v_permlane32_swap_b32_e32 v17, v19
	global_store_dwordx4 v[4:5], v[16:19], off offset:96
	v_pk_mul_f32 v[8:9], v[64:65], v[2:3] op_sel_hi:[1,0]
	v_pk_mul_f32 v[10:11], v[66:67], v[2:3] op_sel_hi:[1,0]
	v_pk_mul_f32 v[12:13], v[68:69], v[2:3] op_sel_hi:[1,0]
	v_pk_mul_f32 v[14:15], v[70:71], v[2:3] op_sel_hi:[1,0]
	v_cvt_pk_bf16_f32 v8, v8, v9
	v_cvt_pk_bf16_f32 v9, v10, v11
	v_cvt_pk_bf16_f32 v10, v12, v13
	v_cvt_pk_bf16_f32 v11, v14, v15
	s_nop 1
	v_permlane32_swap_b32_e32 v8, v10
	v_permlane32_swap_b32_e32 v9, v11
	global_store_dwordx4 v[4:5], v[8:11], off offset:128
	v_pk_mul_f32 v[16:17], v[72:73], v[2:3] op_sel_hi:[1,0]
	v_pk_mul_f32 v[18:19], v[74:75], v[2:3] op_sel_hi:[1,0]
	v_pk_mul_f32 v[20:21], v[76:77], v[2:3] op_sel_hi:[1,0]
	v_pk_mul_f32 v[22:23], v[78:79], v[2:3] op_sel_hi:[1,0]
	v_cvt_pk_bf16_f32 v16, v16, v17
	v_cvt_pk_bf16_f32 v17, v18, v19
	v_cvt_pk_bf16_f32 v18, v20, v21
	v_cvt_pk_bf16_f32 v19, v22, v23
	s_nop 1
	v_permlane32_swap_b32_e32 v16, v18
	v_permlane32_swap_b32_e32 v17, v19
	global_store_dwordx4 v[4:5], v[16:19], off offset:160
	v_pk_mul_f32 v[8:9], v[48:49], v[2:3] op_sel_hi:[1,0]
	v_pk_mul_f32 v[10:11], v[50:51], v[2:3] op_sel_hi:[1,0]
	v_pk_mul_f32 v[12:13], v[52:53], v[2:3] op_sel_hi:[1,0]
	v_pk_mul_f32 v[14:15], v[54:55], v[2:3] op_sel_hi:[1,0]
	v_cvt_pk_bf16_f32 v8, v8, v9
	v_cvt_pk_bf16_f32 v9, v10, v11
	v_cvt_pk_bf16_f32 v10, v12, v13
	v_cvt_pk_bf16_f32 v11, v14, v15
	s_nop 1
	v_permlane32_swap_b32_e32 v8, v10
	v_permlane32_swap_b32_e32 v9, v11
	global_store_dwordx4 v[4:5], v[8:11], off offset:192
	v_pk_mul_f32 v[16:17], v[56:57], v[2:3] op_sel_hi:[1,0]
	v_pk_mul_f32 v[18:19], v[58:59], v[2:3] op_sel_hi:[1,0]
	v_pk_mul_f32 v[20:21], v[60:61], v[2:3] op_sel_hi:[1,0]
	v_pk_mul_f32 v[22:23], v[62:63], v[2:3] op_sel_hi:[1,0]
	v_cvt_pk_bf16_f32 v16, v16, v17
	v_cvt_pk_bf16_f32 v17, v18, v19
	v_cvt_pk_bf16_f32 v18, v20, v21
	v_cvt_pk_bf16_f32 v19, v22, v23
	s_nop 1
	v_permlane32_swap_b32_e32 v16, v18
	v_permlane32_swap_b32_e32 v17, v19
	global_store_dwordx4 v[4:5], v[16:19], off offset:224
	s_and_b64 vcc, exec, s[10:11]
	s_barrier
	s_cbranch_vccnz .LBB0_425
